# P6 load balance: workgroups 0-127 (which own two q-projection units) skip the k up-projection GEMM; workgroups 128-255 run two k units (bid-128, bid)
# speedup vs baseline: 1.0010x; 1.0010x over previous
.LBB0_849:
	s_add_u32 s2, s88, 0xc800200
	s_addc_u32 s3, s89, 0
	v_readlane_b32 s0, v254, 3
	v_mbcnt_lo_u32_b32 v0, -1, 0
	v_mbcnt_hi_u32_b32 v0, -1, v0
	s_cmpk_lt_i32 s54, 0x100
	s_cselect_b64 s[6:7], -1, 0
	v_or_b32_e32 v8, s0, v0
	s_cmpk_lt_i32 s54, 0x80
	v_readfirstlane_b32 s5, v8
	s_cbranch_scc1 .LBB0_873
	s_sub_u32 s54, s54, 0x80
	s_movk_i32 s52, 0x80
	s_ashr_i32 s4, s54, 31
	s_lshr_b32 s0, s4, 29
	s_add_i32 s8, s54, s0
	s_and_b32 s0, s8, -8
	s_sub_i32 s10, s54, s0
	s_cmp_gt_i32 s10, -1
	s_cbranch_scc0 .LBB0_852
	s_lshl_b32 s9, s10, 5
	s_cbranch_execz .LBB0_853
	s_branch .LBB0_854

.LBB0_873:
	s_mov_b32 s52, s90
	s_mov_b32 s54, s92
	v_readlane_b32 s0, v254, 3
	s_add_u32 s46, s88, 0x1c800000
	v_mbcnt_lo_u32_b32 v0, -1, 0
	v_mbcnt_hi_u32_b32 v0, -1, v0
	s_addc_u32 s47, s89, 0
	v_or_b32_e32 v8, s0, v0
	s_andn2_b64 vcc, exec, s[6:7]
	v_readfirstlane_b32 s4, v8
	s_cbranch_vccnz .LBB0_900
	s_ashr_i32 s55, s54, 31
	s_lshr_b32 s0, s55, 29
	s_add_i32 s7, s54, s0
	s_and_b32 s0, s7, -8
	s_sub_i32 s5, s54, s0
	s_cmp_gt_i32 s5, -1
	s_cbranch_scc0 .LBB0_876
	s_lshl_b32 s6, s5, 5
	s_ashr_i32 s0, s7, 3
	s_cbranch_execz .LBB0_877
	s_branch .LBB0_878
